# hand-written RWKV prompt staging (all loads of both items issued up front); sample_gemm via LDS uses s98/s99 only
# speedup vs baseline: 1.1329x; 1.0018x over previous
.LBB0_602:
	s_waitcnt lgkmcnt(0)
	s_add_u32 s24, s0, 0x4c00000
	s_addc_u32 s25, s1, 0
	s_load_dwordx2 s[6:7], s[22:23], 0xa0
	s_add_u32 s26, s0, 0x16480000
	s_addc_u32 s27, s1, 0
	s_add_u32 s38, s0, 0x16504000
	v_readlane_b32 s8, v250, 7
	s_addc_u32 s39, s1, 0
	s_lshl_b32 s12, s8, 2
	s_load_dwordx4 s[8:11], s[22:23], 0xd0
	s_waitcnt lgkmcnt(0)
	s_add_u32 s6, s6, s12
	s_addc_u32 s7, s7, 0
	s_lshl_b32 s40, s34, 6
	s_mov_b32 s41, s73
	s_lshl_b64 s[42:43], s[40:41], 2
	v_and_b32_e32 v24, 15, v2
	s_add_u32 s6, s6, s42
	s_addc_u32 s7, s7, s43
	v_lshlrev_b32_e32 v82, 2, v24
	v_lshlrev_b32_e32 v0, 4, v24
	s_add_i32 s12, s40, s70
	v_lshl_add_u64 v[12:13], s[6:7], 0, v[0:1]
	v_or_b32_e32 v16, s12, v82
	global_load_dwordx4 v[4:7], v0, s[6:7]
	global_load_dwordx4 v[8:11], v0, s[6:7] offset:2048
	s_movk_i32 s6, 0x1000
	v_mov_b32_e32 v17, v1
	v_add_co_u32_e32 v12, vcc, s6, v12
	v_lshlrev_b64 v[20:21], 2, v[16:17]
	s_nop 0
	v_addc_co_u32_e32 v13, vcc, 0, v13, vcc
	v_lshl_add_u64 v[16:17], s[8:9], 0, v[20:21]
	v_lshl_add_u64 v[20:21], s[10:11], 0, v[20:21]
	global_load_dwordx4 v[12:15], v[12:13], off
	v_readlane_b32 s6, v251, 21
	global_load_dwordx4 v[16:19], v[16:17], off
	v_and_b32_e32 v86, 7, v2
	global_load_dwordx4 v[20:23], v[20:21], off
	v_add_u32_e32 v80, s6, v2
	v_ashrrev_i32_e32 v2, 3, v2
	v_readlane_b32 s6, v252, 60
	v_readlane_b32 s7, v251, 22
	v_add_u32_e32 v83, 0, v0
	v_add_u32_e32 v81, s6, v2
	s_lshl_b32 s6, s34, 7
	s_add_u32 s6, s0, s6
	s_addc_u32 s7, s1, 0
	s_add_u32 s44, s6, 0x13300000
	s_addc_u32 s45, s7, 0
	s_add_u32 s60, s6, 0xe8c0800
	s_addc_u32 s61, s7, 0
	s_lshl_b64 s[8:9], s[30:31], 3
	s_add_u32 s87, s8, s34
	s_addc_u32 s90, s9, 0
	v_readlane_b32 s8, v250, 21
	v_lshlrev_b32_e32 v0, 3, v24
	s_add_u32 s8, s87, s8
	v_lshl_add_u64 v[2:3], s[6:7], 0, v[0:1]
	s_mov_b64 s[6:7], 0x12280000
	s_addc_u32 s9, s90, 0
	v_lshl_add_u64 v[88:89], v[2:3], 0, s[6:7]
	s_mov_b64 s[6:7], 0x15400000
	s_lshl_b64 s[62:63], s[8:9], 14
	v_lshl_add_u64 v[90:91], v[2:3], 0, s[6:7]
	v_readlane_b32 s6, v250, 19
	s_add_u32 s41, s6, s30
	v_add_u32_e32 v25, 0xffffff00, v80
	v_readlane_b32 s7, v250, 20
	s_addc_u32 s86, 0, s31
	s_mul_i32 s6, s86, 0x1c00
	s_mul_hi_u32 s7, s41, 0x1c00
	s_movk_i32 s20, 0x600
	v_ashrrev_i32_e32 v117, 4, v25
	v_ashrrev_i32_e32 v119, 4, v80
	v_mov_b32_e32 v2, v1
	v_mov_b32_e32 v3, v1
	s_add_i32 s91, s7, s6
	v_cmp_eq_u32_e64 s[6:7], 0, v24
	v_or_b32_e32 v92, 8, v86
	v_mad_u32_u24 v114, v86, s20, v179
	v_or_b32_e32 v94, 16, v86
	v_mad_u32_u24 v115, v86, s20, v180
	v_or_b32_e32 v96, 24, v86
	v_mad_u32_u24 v116, v86, s20, v181
	v_mul_lo_u32 v118, v117, s20
	v_mul_lo_u32 v120, v119, s20
	s_add_i32 s20, 0, 0x600
	v_mov_b32_e32 v0, v1
	v_mov_b64_e32 v[26:27], v[2:3]
	v_mov_b64_e32 v[30:31], v[2:3]
	v_lshlrev_b32_e32 v84, 3, v86
	s_mov_b32 s35, s73
	s_mul_i32 s94, s41, 0x1c00
	v_cmp_gt_u32_e64 s[8:9], s85, v86
	v_mov_b32_e32 v87, v1
	v_mul_u32_u24_e32 v85, 0x600, v86
	v_cmp_gt_u32_e64 s[10:11], s85, v92
	v_mov_b32_e32 v93, v1
	v_cmp_gt_u32_e64 s[12:13], s85, v94
	v_mov_b32_e32 v95, v1
	v_cmp_gt_u32_e64 s[14:15], s85, v96
	v_mov_b32_e32 v97, v1
	v_cmp_gt_i32_e64 s[16:17], s85, v117
	v_cmp_gt_i32_e64 s[18:19], s85, v119
	v_lshl_add_u32 v121, v86, 2, s66
	v_lshl_add_u32 v122, v86, 5, s20
	s_mov_b32 s64, -1
	s_mov_b64 s[68:69], -1
	v_mov_b64_e32 v[24:25], v[0:1]
	v_mov_b64_e32 v[28:29], v[0:1]
	v_and_b32_e32 v210, 15, v162
	v_readlane_b32 s58, v252, 60
	v_lshrrev_b32_e32 v220, 4, v162
	s_lshr_b32 s58, s58, 1
	s_sub_i32 s58, s58, 16
	v_add_u32_e32 v220, s58, v220
	v_add_u32_e32 v219, s4, v220
	s_lshl_b32 s59, s34, 7
	v_lshl_add_u32 v240, v210, 3, s59
	v_add_u32_e32 v241, 0xd680000, v240
	v_add_u32_e32 v242, 0x10800000, v240
	v_add_u32_e32 v240, 0x1800, v240
	s_lshl_b32 s59, s34, 2
	s_add_u32 s59, s59, 0x11880000
	v_mov_b32_e32 v246, s59
	v_mul_u32_u24_e32 v243, 0x600, v220
	v_lshl_add_u32 v243, v210, 4, v243
	v_lshlrev_b32_e32 v244, 2, v220
	v_add_u32_e32 v244, 0x18000, v244
	s_waitcnt vmcnt(0)
	s_barrier
	s_and_b64 vcc, exec, s[76:77]
	s_mov_b64 s[20:21], -1
	s_cbranch_vccz .LBB0_632

.Lrw_stage2:
	s_add_i32 s95, s64, 1
	s_cmp_ge_u32 s95, s84
	s_cbranch_scc1 .LBB0_653
	s_lshl_b32 s58, s95, 5
	v_add_u32_e32 v37, s58, v219
	v_mul_u32_u24_e32 v32, 0x2600, v37
	v_add_u32_e32 v32, v32, v240
	v_add_u32_e32 v33, 0xffffda00, v32
	v_lshl_add_u32 v34, v37, 10, v241
	v_lshl_add_u32 v35, v37, 10, v242
	v_lshl_add_u32 v36, v37, 5, v246
	global_load_dwordx2 v[222:223], v32, s[24:25]
	global_load_dwordx2 v[224:225], v32, s[24:25] offset:1024
	global_load_dwordx2 v[226:227], v32, s[24:25] offset:2048
	v_mov_b32_e32 v228, 0
	v_mov_b32_e32 v229, 0
	v_mov_b32_e32 v230, 0
	v_mov_b32_e32 v231, 0
	v_mov_b32_e32 v232, 0
	v_mov_b32_e32 v233, 0
	s_mov_b64 s[70:71], exec
	s_cmp_lg_u32 s95, 0
	s_cbranch_scc1 .Lrw_stage2_prev
	v_cmp_ne_u32_e32 vcc, 0, v220
	s_and_b64 exec, exec, vcc
.Lrw_stage2_prev:
	global_load_dwordx2 v[228:229], v33, s[24:25]
	global_load_dwordx2 v[230:231], v33, s[24:25] offset:1024
	global_load_dwordx2 v[232:233], v33, s[24:25] offset:2048
	s_mov_b64 exec, s[70:71]
	global_load_dwordx2 v[234:235], v34, s[24:25]
	global_load_dwordx2 v[236:237], v35, s[24:25]
	global_load_dword v238, v36, s[24:25]
	v_add_u32_e32 v36, 0x84000, v36
	global_load_dword v239, v36, s[24:25]
	s_lshl_b32 s58, s95, 5
	s_add_u32 s58, s58, 16
	v_add_u32_e32 v37, s58, v219
	v_mul_u32_u24_e32 v32, 0x2600, v37
	v_add_u32_e32 v32, v32, v240
	v_add_u32_e32 v33, 0xffffda00, v32
	v_lshl_add_u32 v34, v37, 10, v241
	v_lshl_add_u32 v35, v37, 10, v242
	v_lshl_add_u32 v36, v37, 5, v246
	global_load_dwordx2 v[182:183], v32, s[24:25]
	global_load_dwordx2 v[184:185], v32, s[24:25] offset:1024
	global_load_dwordx2 v[186:187], v32, s[24:25] offset:2048
	v_mov_b32_e32 v188, 0
	v_mov_b32_e32 v189, 0
	v_mov_b32_e32 v190, 0
	v_mov_b32_e32 v191, 0
	v_mov_b32_e32 v192, 0
	v_mov_b32_e32 v193, 0
	global_load_dwordx2 v[188:189], v33, s[24:25]
	global_load_dwordx2 v[190:191], v33, s[24:25] offset:1024
	global_load_dwordx2 v[192:193], v33, s[24:25] offset:2048
	global_load_dwordx2 v[194:195], v34, s[24:25]
	global_load_dwordx2 v[196:197], v35, s[24:25]
	global_load_dword v198, v36, s[24:25]
	v_add_u32_e32 v36, 0x84000, v36
	global_load_dword v199, v36, s[24:25]
	s_and_b32 s58, s95, 1
	s_mul_i32 s59, s58, 0xc000
	s_lshl_b32 s58, s58, 7
	v_add_u32_e32 v245, s59, v243
	v_add_u32_e32 v247, s58, v244
	s_waitcnt vmcnt(10)
	v_lshlrev_b32_e32 v32, 16, v222
	v_and_b32_e32 v33, 0xffff0000, v222
	v_lshlrev_b32_e32 v34, 16, v223
	v_and_b32_e32 v35, 0xffff0000, v223
	v_lshlrev_b32_e32 v36, 16, v228
	v_and_b32_e32 v37, 0xffff0000, v228
	v_lshlrev_b32_e32 v38, 16, v229
	v_and_b32_e32 v39, 0xffff0000, v229
	v_sub_f32_e32 v36, v36, v32
	v_sub_f32_e32 v37, v37, v33
	v_sub_f32_e32 v38, v38, v34
	v_sub_f32_e32 v39, v39, v35
	v_pk_fma_f32 v[36:37], v[4:5], v[36:37], v[32:33]
	v_pk_fma_f32 v[38:39], v[6:7], v[38:39], v[34:35]
	ds_write_b128 v245, v[36:39] offset:1024
	v_lshlrev_b32_e32 v32, 16, v226
	v_and_b32_e32 v33, 0xffff0000, v226
	v_lshlrev_b32_e32 v34, 16, v227
	v_and_b32_e32 v35, 0xffff0000, v227
	v_lshlrev_b32_e32 v40, 16, v232
	v_and_b32_e32 v41, 0xffff0000, v232
	v_lshlrev_b32_e32 v42, 16, v233
	v_and_b32_e32 v43, 0xffff0000, v233
	v_sub_f32_e32 v40, v40, v32
	v_sub_f32_e32 v41, v41, v33
	v_sub_f32_e32 v42, v42, v34
	v_sub_f32_e32 v43, v43, v35
	v_pk_fma_f32 v[40:41], v[12:13], v[40:41], v[32:33]
	v_pk_fma_f32 v[42:43], v[14:15], v[42:43], v[34:35]
	ds_write_b128 v245, v[40:43] offset:1280
	v_lshlrev_b32_e32 v32, 16, v224
	v_and_b32_e32 v33, 0xffff0000, v224
	v_lshlrev_b32_e32 v34, 16, v225
	v_and_b32_e32 v35, 0xffff0000, v225
	v_lshlrev_b32_e32 v44, 16, v230
	v_and_b32_e32 v45, 0xffff0000, v230
	v_lshlrev_b32_e32 v46, 16, v231
	v_and_b32_e32 v47, 0xffff0000, v231
	v_sub_f32_e32 v44, v44, v32
	v_sub_f32_e32 v45, v45, v33
	v_sub_f32_e32 v46, v46, v34
	v_sub_f32_e32 v47, v47, v35
	v_pk_fma_f32 v[44:45], v[8:9], v[44:45], v[32:33]
	v_pk_fma_f32 v[46:47], v[10:11], v[46:47], v[34:35]
	v_lshlrev_b32_e32 v60, 16, v234
	v_and_b32_e32 v61, 0xffff0000, v234
	v_lshlrev_b32_e32 v62, 16, v235
	v_and_b32_e32 v63, 0xffff0000, v235
	v_mul_f32_e32 v60, 0x3fb8aa3b, v60
	v_mul_f32_e32 v61, 0x3fb8aa3b, v61
	v_mul_f32_e32 v62, 0x3fb8aa3b, v62
	v_mul_f32_e32 v63, 0x3fb8aa3b, v63
	v_exp_f32_e32 v60, v60
	v_exp_f32_e32 v61, v61
	v_exp_f32_e32 v62, v62
	v_exp_f32_e32 v63, v63
	v_pk_mul_f32 v[48:49], v[16:17], v[44:45]
	v_pk_mul_f32 v[50:51], v[18:19], v[46:47]
	v_pk_mul_f32 v[48:49], v[48:49], v[238:239] op_sel_hi:[1,0]
	v_pk_mul_f32 v[50:51], v[50:51], v[238:239] op_sel_hi:[1,0]
	ds_write_b128 v245, v[48:51] offset:256
	v_lshlrev_b32_e32 v52, 16, v236
	v_and_b32_e32 v53, 0xffff0000, v236
	v_lshlrev_b32_e32 v54, 16, v237
	v_and_b32_e32 v55, 0xffff0000, v237
	v_pk_mul_f32 v[56:57], v[48:49], v[52:53]
	v_pk_mul_f32 v[58:59], v[50:51], v[54:55]
	ds_write_b128 v245, v[56:59] offset:512
	v_pk_add_f32 v[52:53], v[52:53], -1.0 op_sel_hi:[1,0]
	v_pk_add_f32 v[54:55], v[54:55], -1.0 op_sel_hi:[1,0]
	v_pk_fma_f32 v[52:53], v[20:21], v[52:53], 1.0 op_sel_hi:[1,1,0]
	v_pk_fma_f32 v[54:55], v[22:23], v[54:55], 1.0 op_sel_hi:[1,1,0]
	v_pk_mul_f32 v[52:53], v[44:45], v[52:53]
	v_pk_mul_f32 v[54:55], v[46:47], v[54:55]
	ds_write_b128 v245, v[52:55] offset:768
	ds_write_b128 v245, v[60:63]
	ds_write_b32 v247, v239
	s_waitcnt vmcnt(0)
	v_lshlrev_b32_e32 v32, 16, v182
	v_and_b32_e32 v33, 0xffff0000, v182
	v_lshlrev_b32_e32 v34, 16, v183
	v_and_b32_e32 v35, 0xffff0000, v183
	v_lshlrev_b32_e32 v36, 16, v188
	v_and_b32_e32 v37, 0xffff0000, v188
	v_lshlrev_b32_e32 v38, 16, v189
	v_and_b32_e32 v39, 0xffff0000, v189
	v_sub_f32_e32 v36, v36, v32
	v_sub_f32_e32 v37, v37, v33
	v_sub_f32_e32 v38, v38, v34
	v_sub_f32_e32 v39, v39, v35
	v_pk_fma_f32 v[36:37], v[4:5], v[36:37], v[32:33]
	v_pk_fma_f32 v[38:39], v[6:7], v[38:39], v[34:35]
	ds_write_b128 v245, v[36:39] offset:25600
	v_lshlrev_b32_e32 v32, 16, v186
	v_and_b32_e32 v33, 0xffff0000, v186
	v_lshlrev_b32_e32 v34, 16, v187
	v_and_b32_e32 v35, 0xffff0000, v187
	v_lshlrev_b32_e32 v40, 16, v192
	v_and_b32_e32 v41, 0xffff0000, v192
	v_lshlrev_b32_e32 v42, 16, v193
	v_and_b32_e32 v43, 0xffff0000, v193
	v_sub_f32_e32 v40, v40, v32
	v_sub_f32_e32 v41, v41, v33
	v_sub_f32_e32 v42, v42, v34
	v_sub_f32_e32 v43, v43, v35
	v_pk_fma_f32 v[40:41], v[12:13], v[40:41], v[32:33]
	v_pk_fma_f32 v[42:43], v[14:15], v[42:43], v[34:35]
	ds_write_b128 v245, v[40:43] offset:25856
	v_lshlrev_b32_e32 v32, 16, v184
	v_and_b32_e32 v33, 0xffff0000, v184
	v_lshlrev_b32_e32 v34, 16, v185
	v_and_b32_e32 v35, 0xffff0000, v185
	v_lshlrev_b32_e32 v44, 16, v190
	v_and_b32_e32 v45, 0xffff0000, v190
	v_lshlrev_b32_e32 v46, 16, v191
	v_and_b32_e32 v47, 0xffff0000, v191
	v_sub_f32_e32 v44, v44, v32
	v_sub_f32_e32 v45, v45, v33
	v_sub_f32_e32 v46, v46, v34
	v_sub_f32_e32 v47, v47, v35
	v_pk_fma_f32 v[44:45], v[8:9], v[44:45], v[32:33]
	v_pk_fma_f32 v[46:47], v[10:11], v[46:47], v[34:35]
	v_lshlrev_b32_e32 v60, 16, v194
	v_and_b32_e32 v61, 0xffff0000, v194
	v_lshlrev_b32_e32 v62, 16, v195
	v_and_b32_e32 v63, 0xffff0000, v195
	v_mul_f32_e32 v60, 0x3fb8aa3b, v60
	v_mul_f32_e32 v61, 0x3fb8aa3b, v61
	v_mul_f32_e32 v62, 0x3fb8aa3b, v62
	v_mul_f32_e32 v63, 0x3fb8aa3b, v63
	v_exp_f32_e32 v60, v60
	v_exp_f32_e32 v61, v61
	v_exp_f32_e32 v62, v62
	v_exp_f32_e32 v63, v63
	v_pk_mul_f32 v[48:49], v[16:17], v[44:45]
	v_pk_mul_f32 v[50:51], v[18:19], v[46:47]
	v_pk_mul_f32 v[48:49], v[48:49], v[198:199] op_sel_hi:[1,0]
	v_pk_mul_f32 v[50:51], v[50:51], v[198:199] op_sel_hi:[1,0]
	ds_write_b128 v245, v[48:51] offset:24832
	v_lshlrev_b32_e32 v52, 16, v196
	v_and_b32_e32 v53, 0xffff0000, v196
	v_lshlrev_b32_e32 v54, 16, v197
	v_and_b32_e32 v55, 0xffff0000, v197
	v_pk_mul_f32 v[56:57], v[48:49], v[52:53]
	v_pk_mul_f32 v[58:59], v[50:51], v[54:55]
	ds_write_b128 v245, v[56:59] offset:25088
	v_pk_add_f32 v[52:53], v[52:53], -1.0 op_sel_hi:[1,0]
	v_pk_add_f32 v[54:55], v[54:55], -1.0 op_sel_hi:[1,0]
	v_pk_fma_f32 v[52:53], v[20:21], v[52:53], 1.0 op_sel_hi:[1,1,0]
	v_pk_fma_f32 v[54:55], v[22:23], v[54:55], 1.0 op_sel_hi:[1,1,0]
	v_pk_mul_f32 v[52:53], v[44:45], v[52:53]
	v_pk_mul_f32 v[54:55], v[46:47], v[54:55]
	ds_write_b128 v245, v[52:55] offset:25344
	ds_write_b128 v245, v[60:63] offset:24576
	ds_write_b32 v247, v199 offset:64
	s_branch .LBB0_653

.LBB0_632:
	s_and_b64 vcc, exec, s[36:37]
	s_cbranch_vccnz .Lrw_stage2_skip
	s_and_b64 vcc, exec, s[20:21]
	s_cbranch_vccnz .Lrw_stage2

.LBB0_683:
	v_readfirstlane_b32 s98, v38
	v_readfirstlane_b32 s99, v39
	v_readlane_b32 vcc_lo, v252, 60
	s_lshr_b32 vcc_lo, vcc_lo, 3
	s_and_b32 s40, vcc_lo, 1
	s_lshl_b32 s41, s36, 4
	s_mul_i32 s40, s40, s41
	s_sub_u32 s98, s98, s40
	s_subb_u32 s99, s99, 0
	v_lshl_add_u32 v106, vcc_lo, 6, v162
	v_lshrrev_b32_e32 v107, 5, v106
	v_and_b32_e32 v108, 31, v106
	v_lshlrev_b32_e32 v108, 4, v108
	v_mov_b32_e32 v109, 0
	v_mov_b64_e32 v[112:113], s[98:99]
	v_lshl_add_u64 v[112:113], v[112:113], 0, v[108:109]
	v_mad_u64_u32 v[110:111], s[40:41], s36, v107, v[112:113]
	v_readfirstlane_b32 s98, v40
	v_readfirstlane_b32 s99, v41
	s_lshr_b32 s40, vcc_lo, 1
	s_lshl_b32 s41, s20, 4
	s_mul_i32 s40, s40, s41
	s_add_u32 s40, s40, 0x100
	s_sub_u32 s98, s98, s40
	s_subb_u32 s99, s99, 0
	v_mov_b64_e32 v[112:113], s[98:99]
	v_lshl_add_u64 v[112:113], v[112:113], 0, v[108:109]
	v_mad_u64_u32 v[114:115], s[40:41], s20, v107, v[112:113]
	s_lshl_b32 s40, s36, 4
	s_mov_b32 s41, 0
	v_lshl_add_u64 v[116:117], v[110:111], 0, s[40:41]
	s_lshl_b32 s40, s20, 4
	v_lshl_add_u64 v[118:119], v[114:115], 0, s[40:41]
	v_lshl_add_u64 v[120:121], v[118:119], 0, s[40:41]
	v_lshl_add_u64 v[122:123], v[120:121], 0, s[40:41]
	v_mul_u32_u24_e32 v124, 0x210, v107
	v_add_u32_e32 v124, v124, v108
	v_and_b32_e32 v125, 15, v162
	v_lshrrev_b32_e32 v126, 4, v162
	s_and_b32 s40, vcc_lo, 1
	s_lshl_b32 s40, s40, 4
	v_add_u32_e32 v127, s40, v125
	v_mul_u32_u24_e32 v127, 0x210, v127
	v_lshl_add_u32 v127, v126, 4, v127
	s_lshr_b32 s40, vcc_lo, 1
	s_lshl_b32 s40, s40, 4
	v_add_u32_e32 v128, s40, v125
	v_mul_u32_u24_e32 v128, 0x210, v128
	v_lshl_add_u32 v128, v126, 4, v128
	v_add_u32_e32 v128, 0x4200, v128
	global_load_dwordx4 v[82:85], v[110:111], off
	global_load_dwordx4 v[86:89], v[116:117], off
	global_load_dwordx4 v[90:93], v[114:115], off
	global_load_dwordx4 v[94:97], v[118:119], off
	global_load_dwordx4 v[98:101], v[120:121], off
	global_load_dwordx4 v[102:105], v[122:123], off
	v_lshl_add_u64 v[110:111], v[110:111], 0, s[50:51]
	v_lshl_add_u64 v[116:117], v[116:117], 0, s[50:51]
	v_lshl_add_u64 v[114:115], v[114:115], 0, s[50:51]
	v_lshl_add_u64 v[118:119], v[118:119], 0, s[50:51]
	v_lshl_add_u64 v[120:121], v[120:121], 0, s[50:51]
	v_lshl_add_u64 v[122:123], v[122:123], 0, s[50:51]
	s_mov_b32 s40, 0
